# C4: norm phases: wave reduction via DPP+permlane swaps instead of 6 ds_bpermute round trips; gmlp LN gamma loads hoisted
# speedup vs baseline: 1.0216x; 1.0008x over previous
.LBB0_23:
	s_waitcnt vmcnt(3)
	v_mul_f32_e32 v0, v47, v47
	v_mul_f32_e32 v64, v49, v49
	v_fmac_f32_e32 v0, v46, v46
	v_fmac_f32_e32 v64, v48, v48
	v_add_f32_e32 v0, v0, v64
	s_waitcnt vmcnt(2)
	v_mul_f32_e32 v64, v43, v43
	v_mul_f32_e32 v65, v45, v45
	v_fmac_f32_e32 v64, v42, v42
	v_fmac_f32_e32 v65, v44, v44
	v_add_f32_e32 v64, v64, v65
	v_add_f32_e32 v0, v0, v64
	s_waitcnt vmcnt(1)
	v_mul_f32_e32 v64, v39, v39
	v_mul_f32_e32 v65, v41, v41
	v_fmac_f32_e32 v64, v38, v38
	v_fmac_f32_e32 v65, v40, v40
	v_add_f32_e32 v64, v64, v65
	v_add_f32_e32 v0, v0, v64
	s_waitcnt vmcnt(0)
	v_mul_f32_e32 v64, v35, v35
	v_mul_f32_e32 v65, v37, v37
	v_fmac_f32_e32 v64, v34, v34
	v_fmac_f32_e32 v65, v36, v36
	v_add_f32_e32 v64, v64, v65
	v_add_f32_e32 v0, v0, v64
	s_nop 1
	v_add_f32_dpp v0, v0, v0 quad_perm:[1,0,3,2] row_mask:0xf bank_mask:0xf
	s_nop 1
	v_add_f32_dpp v0, v0, v0 quad_perm:[2,3,0,1] row_mask:0xf bank_mask:0xf
	s_nop 1
	v_add_f32_dpp v0, v0, v0 row_half_mirror row_mask:0xf bank_mask:0xf
	s_nop 1
	v_add_f32_dpp v0, v0, v0 row_mirror row_mask:0xf bank_mask:0xf
	v_mov_b32_e32 v64, v0
	s_nop 1
	v_permlane16_swap_b32_e32 v0, v64
	v_add_f32_e32 v0, v0, v64
	v_mov_b32_e32 v64, v0
	s_nop 1
	v_permlane32_swap_b32_e32 v0, v64
	v_add_f32_e32 v0, v0, v64
	v_readlane_b32 s20, v255, 5
	s_mov_b32 s16, 0xb400000
	v_readlane_b32 s21, v255, 6
	s_add_i32 s11, s11, s82
	s_nop 0
	v_lshl_add_u64 v[52:53], v[52:53], 0, s[20:21]
	v_readlane_b32 s20, v254, 57
	v_readlane_b32 s21, v254, 58
	s_cmp_lt_i32 s11, s2
	v_fmamk_f32 v0, v0, 0x3a800000, v177
	v_rsq_f32_e32 v0, v0
	s_nop 0
	v_pk_mul_f32 v[42:43], v[42:43], v[0:1] op_sel_hi:[1,0]
	v_pk_mul_f32 v[44:45], v[44:45], v[0:1] op_sel_hi:[1,0]
	v_pk_mul_f32 v[46:47], v[46:47], v[0:1] op_sel_hi:[1,0]
	v_pk_mul_f32 v[48:49], v[48:49], v[0:1] op_sel_hi:[1,0]
	v_pk_fma_f32 v[64:65], v[8:9], v[44:45], v[24:25]
	v_pk_fma_f32 v[44:45], v[6:7], v[42:43], v[22:23]
	v_pk_fma_f32 v[48:49], v[4:5], v[48:49], v[32:33]
	v_pk_fma_f32 v[46:47], v[2:3], v[46:47], v[30:31]
	v_pk_mul_f32 v[34:35], v[34:35], v[0:1] op_sel_hi:[1,0]
	v_cvt_pk_bf16_f32 v42, v46, v47
	v_cvt_pk_bf16_f32 v43, v48, v49
	v_cvt_pk_bf16_f32 v44, v44, v45
	v_cvt_pk_bf16_f32 v45, v64, v65
	s_load_dwordx2 s[28:29], s[36:37], 0xb0
	v_pk_mul_f32 v[36:37], v[36:37], v[0:1] op_sel_hi:[1,0]
	v_pk_mul_f32 v[38:39], v[38:39], v[0:1] op_sel_hi:[1,0]
	v_pk_mul_f32 v[40:41], v[40:41], v[0:1] op_sel_hi:[1,0]
	v_pk_fma_f32 v[38:39], v[10:11], v[38:39], v[26:27]
	s_waitcnt lgkmcnt(0)
	v_lshl_add_u64 v[46:47], s[28:29], 0, v[54:55]
	v_add_co_u32_e32 v46, vcc, s16, v46
	v_lshl_add_u64 v[54:55], v[54:55], 0, s[20:21]
	s_nop 0
	v_addc_co_u32_e32 v47, vcc, 0, v47, vcc
	global_store_dwordx4 v[46:47], v[42:45], off
	v_pk_fma_f32 v[40:41], v[12:13], v[40:41], v[28:29]
	s_nop 0
	v_pk_fma_f32 v[42:43], v[16:17], v[36:37], v[20:21]
	v_pk_fma_f32 v[36:37], v[14:15], v[34:35], v[18:19]
	v_cvt_pk_bf16_f32 v34, v38, v39
	v_cvt_pk_bf16_f32 v35, v40, v41
	s_nop 0
	v_cvt_pk_bf16_f32 v36, v36, v37
	v_cvt_pk_bf16_f32 v37, v42, v43
	global_store_dwordx4 v[46:47], v[34:37], off offset:1024
	s_cbranch_scc0 .LBB0_26

.LBB0_257:
	v_readfirstlane_b32 s22, v140
	s_ashr_i32 s10, s22, 7
	s_ashr_i32 s11, s10, 31
	s_lshl_b64 s[20:21], s[10:11], 15
	v_and_or_b32 v80, s22, 64, v145
	v_lshl_add_u64 v[18:19], v[74:75], 0, s[20:21]
	v_lshlrev_b32_e32 v0, 8, v80
	s_waitcnt vmcnt(2)
	v_or_b32_e32 v22, 0x1000, v0
	v_mov_b32_e32 v23, v1
	s_waitcnt vmcnt(0)
	v_lshl_add_u64 v[14:15], v[18:19], 0, s[34:35]
	v_lshl_add_u64 v[2:3], v[18:19], 0, v[22:23]
	v_or_b32_e32 v26, 0x2000, v0
	v_mov_b32_e32 v27, v1
	v_lshl_add_u64 v[6:7], v[14:15], 0, v[22:23]
	v_lshl_add_u64 v[20:21], v[18:19], 0, v[0:1]
	global_load_dwordx4 v[54:57], v[2:3], off
	v_or_b32_e32 v0, 0x3000, v0
	global_load_dwordx4 v[6:9], v[6:7], off
	v_lshl_add_u64 v[2:3], v[18:19], 0, v[26:27]
	v_lshl_add_u64 v[10:11], v[14:15], 0, v[26:27]
	s_mov_b64 s[20:21], 0xc0
	v_mov_b64_e32 v[82:83], s[72:73]
	global_load_dwordx4 v[58:61], v[2:3], off
	v_lshl_add_u64 v[14:15], v[14:15], 0, v[0:1]
	global_load_dwordx4 v[10:13], v[10:11], off
	v_lshl_add_u64 v[2:3], v[18:19], 0, v[0:1]
	v_lshl_add_u64 v[30:31], v[18:19], 0, s[20:21]
	v_mad_i64_i32 v[66:67], s[20:21], v87, s64, v[82:83]
	global_load_dwordx4 v[62:65], v[2:3], off
	v_lshl_add_u64 v[66:67], v[76:77], 1, v[66:67]
	global_load_dwordx4 v[14:17], v[14:15], off
	v_lshl_add_u64 v[2:3], v[18:19], 0, 64
	s_mov_b64 s[20:21], 0x1000
	v_lshl_add_u64 v[4:5], v[2:3], 0, v[22:23]
	v_lshl_add_u64 v[96:97], v[66:67], 0, s[20:21]
	v_add_co_u32_e32 v66, vcc, s26, v66
	global_load_dwordx4 v[50:53], v[20:21], off
	global_load_dwordx4 v[38:41], v[4:5], off
	v_lshl_add_u64 v[4:5], v[2:3], 0, v[26:27]
	v_lshl_add_u64 v[2:3], v[2:3], 0, v[0:1]
	v_lshl_add_u64 v[22:23], v[30:31], 0, v[22:23]
	v_lshl_add_u64 v[26:27], v[30:31], 0, v[26:27]
	v_lshl_add_u64 v[30:31], v[30:31], 0, v[0:1]
	v_addc_co_u32_e32 v67, vcc, 0, v67, vcc
	global_load_dwordx4 v[34:37], v[20:21], off offset:64
	global_load_dwordx4 v[42:45], v[4:5], off
	global_load_dwordx4 v[46:49], v[2:3], off
	s_mul_i32 s11, s10, 0x4800
	global_load_dwordx4 v[2:5], v[20:21], off offset:128
	s_add_i32 s16, s16, s96
	global_load_dwordx4 v[18:21], v[20:21], off offset:192
	v_add_u32_e32 v87, s23, v87
	global_load_dwordx4 v[22:25], v[22:23], off
	s_nop 0
	global_load_dwordx4 v[26:29], v[26:27], off
	s_nop 0
	global_load_dwordx4 v[30:33], v[30:31], off
	s_nop 0
	global_load_dwordx4 v[66:69], v[66:67], off
	s_nop 0
	global_load_dwordx4 v[70:73], v[96:97], off offset:48
	global_load_dwordx4 v[88:91], v[96:97], off offset:32
	global_load_dwordx4 v[92:95], v[96:97], off offset:16
	s_waitcnt vmcnt(3)
	v_lshlrev_b32_e32 v150, 16, v66
	v_and_b32_e32 v149, 0xffff0000, v66
	v_lshlrev_b32_e32 v148, 16, v67
	v_and_b32_e32 v146, 0xffff0000, v67
	v_lshlrev_b32_e32 v137, 16, v68
	v_and_b32_e32 v136, 0xffff0000, v68
	v_lshlrev_b32_e32 v135, 16, v69
	v_and_b32_e32 v134, 0xffff0000, v69
	s_waitcnt vmcnt(0)
	v_lshlrev_b32_e32 v133, 16, v92
	v_and_b32_e32 v132, 0xffff0000, v92
	v_lshlrev_b32_e32 v131, 16, v93
	v_and_b32_e32 v130, 0xffff0000, v93
	v_lshlrev_b32_e32 v129, 16, v94
	v_and_b32_e32 v128, 0xffff0000, v94
	v_lshlrev_b32_e32 v127, 16, v95
	v_and_b32_e32 v126, 0xffff0000, v95
	v_lshlrev_b32_e32 v125, 16, v88
	v_and_b32_e32 v124, 0xffff0000, v88
	v_lshlrev_b32_e32 v123, 16, v89
	v_and_b32_e32 v122, 0xffff0000, v89
	v_lshlrev_b32_e32 v121, 16, v90
	v_and_b32_e32 v120, 0xffff0000, v90
	v_lshlrev_b32_e32 v119, 16, v91
	v_and_b32_e32 v118, 0xffff0000, v91
	v_lshlrev_b32_e32 v117, 16, v70
	v_and_b32_e32 v116, 0xffff0000, v70
	v_lshlrev_b32_e32 v115, 16, v71
	v_and_b32_e32 v114, 0xffff0000, v71
	v_lshlrev_b32_e32 v113, 16, v72
	v_and_b32_e32 v112, 0xffff0000, v72
	v_lshlrev_b32_e32 v111, 16, v73
	v_and_b32_e32 v110, 0xffff0000, v73
	global_load_dwordx4 v[66:69], v[96:97], off offset:112
	global_load_dwordx4 v[70:73], v[96:97], off offset:96
	global_load_dwordx4 v[88:91], v[96:97], off offset:80
	global_load_dwordx4 v[92:95], v[96:97], off offset:64
	s_waitcnt vmcnt(3)
	v_and_b32_e32 v0, 0xffff0000, v66
	s_waitcnt vmcnt(2)
	v_lshlrev_b32_e32 v81, 16, v73
	s_waitcnt vmcnt(1)
	v_lshlrev_b32_e32 v101, 16, v88
	v_and_b32_e32 v100, 0xffff0000, v88
	v_lshlrev_b32_e32 v99, 16, v89
	v_and_b32_e32 v98, 0xffff0000, v89
	v_lshlrev_b32_e32 v89, 16, v72
	v_and_b32_e32 v88, 0xffff0000, v72
	v_lshlrev_b32_e32 v72, 16, v66
	v_add_f32_e32 v66, 0, v150
	v_add_f32_e32 v66, v66, v149
	v_add_f32_e32 v66, v66, v148
	v_add_f32_e32 v66, v66, v146
	v_add_f32_e32 v66, v66, v137
	v_add_f32_e32 v66, v66, v136
	v_add_f32_e32 v66, v66, v135
	v_add_f32_e32 v66, v66, v134
	v_add_f32_e32 v66, v66, v133
	v_add_f32_e32 v66, v66, v132
	v_add_f32_e32 v66, v66, v131
	v_add_f32_e32 v66, v66, v130
	v_add_f32_e32 v66, v66, v129
	v_add_f32_e32 v66, v66, v128
	v_add_f32_e32 v66, v66, v127
	v_add_f32_e32 v66, v66, v126
	v_add_f32_e32 v66, v66, v125
	v_add_f32_e32 v66, v66, v124
	v_add_f32_e32 v66, v66, v123
	v_add_f32_e32 v66, v66, v122
	v_add_f32_e32 v66, v66, v121
	v_add_f32_e32 v66, v66, v120
	v_add_f32_e32 v66, v66, v119
	v_add_f32_e32 v66, v66, v118
	v_add_f32_e32 v66, v66, v117
	v_add_f32_e32 v66, v66, v116
	v_add_f32_e32 v66, v66, v115
	v_add_f32_e32 v66, v66, v114
	v_add_f32_e32 v66, v66, v113
	v_add_f32_e32 v66, v66, v112
	v_add_f32_e32 v66, v66, v111
	s_waitcnt vmcnt(0)
	v_lshlrev_b32_e32 v109, 16, v92
	v_add_f32_e32 v66, v66, v110
	v_and_b32_e32 v108, 0xffff0000, v92
	v_add_f32_e32 v66, v66, v109
	v_lshlrev_b32_e32 v107, 16, v93
	v_add_f32_e32 v66, v66, v108
	v_and_b32_e32 v106, 0xffff0000, v93
	v_add_f32_e32 v66, v66, v107
	v_lshlrev_b32_e32 v105, 16, v94
	v_add_f32_e32 v66, v66, v106
	v_and_b32_e32 v104, 0xffff0000, v94
	v_add_f32_e32 v66, v66, v105
	v_lshlrev_b32_e32 v103, 16, v95
	v_add_f32_e32 v66, v66, v104
	v_and_b32_e32 v102, 0xffff0000, v95
	v_add_f32_e32 v66, v66, v103
	v_add_f32_e32 v66, v66, v102
	v_add_f32_e32 v66, v66, v101
	v_add_f32_e32 v66, v66, v100
	v_add_f32_e32 v66, v66, v99
	v_lshlrev_b32_e32 v97, 16, v90
	v_add_f32_e32 v66, v66, v98
	v_and_b32_e32 v96, 0xffff0000, v90
	v_add_f32_e32 v66, v66, v97
	v_lshlrev_b32_e32 v95, 16, v91
	v_add_f32_e32 v66, v66, v96
	v_and_b32_e32 v94, 0xffff0000, v91
	v_add_f32_e32 v66, v66, v95
	v_lshlrev_b32_e32 v93, 16, v70
	v_add_f32_e32 v66, v66, v94
	v_and_b32_e32 v92, 0xffff0000, v70
	v_add_f32_e32 v66, v66, v93
	v_lshlrev_b32_e32 v91, 16, v71
	v_add_f32_e32 v66, v66, v92
	v_and_b32_e32 v90, 0xffff0000, v71
	v_add_f32_e32 v66, v66, v91
	v_add_f32_e32 v66, v66, v90
	v_add_f32_e32 v66, v66, v89
	v_add_f32_e32 v66, v66, v88
	v_and_b32_e32 v73, 0xffff0000, v73
	v_add_f32_e32 v66, v66, v81
	v_add_f32_e32 v66, v66, v73
	v_add_f32_e32 v66, v66, v72
	v_add_f32_e32 v70, v66, v0
	v_and_b32_e32 v66, 0xffff0000, v67
	v_lshlrev_b32_e32 v67, 16, v67
	v_and_b32_e32 v156, 0xffff0000, v68
	v_lshlrev_b32_e32 v157, 16, v68
	v_add_f32_e32 v68, v70, v67
	v_add_f32_e32 v68, v68, v66
	v_add_f32_e32 v68, v68, v157
	v_lshlrev_b32_e32 v153, 16, v69
	v_add_f32_e32 v68, v68, v156
	v_and_b32_e32 v152, 0xffff0000, v69
	v_add_f32_e32 v68, v68, v153
	v_add_f32_e32 v68, v68, v152
	v_fmac_f32_e32 v149, 0xbc800000, v68
	v_fmac_f32_e32 v150, 0xbc800000, v68
	v_mul_f32_e32 v69, v149, v149
	v_fmac_f32_e32 v69, v150, v150
	v_fmac_f32_e32 v148, 0xbc800000, v68
	v_fmac_f32_e32 v69, v148, v148
	v_fmac_f32_e32 v146, 0xbc800000, v68
	v_fmac_f32_e32 v69, v146, v146
	v_fmac_f32_e32 v137, 0xbc800000, v68
	v_fmac_f32_e32 v69, v137, v137
	v_fmac_f32_e32 v136, 0xbc800000, v68
	v_fmac_f32_e32 v69, v136, v136
	v_fmac_f32_e32 v135, 0xbc800000, v68
	v_fmac_f32_e32 v69, v135, v135
	v_fmac_f32_e32 v134, 0xbc800000, v68
	v_fmac_f32_e32 v69, v134, v134
	v_fmac_f32_e32 v133, 0xbc800000, v68
	v_fmac_f32_e32 v69, v133, v133
	v_fmac_f32_e32 v132, 0xbc800000, v68
	v_fmac_f32_e32 v69, v132, v132
	v_fmac_f32_e32 v131, 0xbc800000, v68
	v_fmac_f32_e32 v69, v131, v131
	v_fmac_f32_e32 v130, 0xbc800000, v68
	v_fmac_f32_e32 v69, v130, v130
	v_fmac_f32_e32 v129, 0xbc800000, v68
	v_fmac_f32_e32 v69, v129, v129
	v_fmac_f32_e32 v128, 0xbc800000, v68
	v_fmac_f32_e32 v69, v128, v128
	v_fmac_f32_e32 v127, 0xbc800000, v68
	v_fmac_f32_e32 v69, v127, v127
	v_fmac_f32_e32 v126, 0xbc800000, v68
	v_fmac_f32_e32 v69, v126, v126
	v_fmac_f32_e32 v125, 0xbc800000, v68
	v_fmac_f32_e32 v69, v125, v125
	v_fmac_f32_e32 v124, 0xbc800000, v68
	v_fmac_f32_e32 v69, v124, v124
	v_fmac_f32_e32 v123, 0xbc800000, v68
	v_fmac_f32_e32 v69, v123, v123
	v_fmac_f32_e32 v122, 0xbc800000, v68
	v_fmac_f32_e32 v69, v122, v122
	v_fmac_f32_e32 v121, 0xbc800000, v68
	v_fmac_f32_e32 v69, v121, v121
	v_fmac_f32_e32 v120, 0xbc800000, v68
	v_fmac_f32_e32 v69, v120, v120
	v_fmac_f32_e32 v119, 0xbc800000, v68
	v_fmac_f32_e32 v69, v119, v119
	v_fmac_f32_e32 v118, 0xbc800000, v68
	v_fmac_f32_e32 v69, v118, v118
	v_fmac_f32_e32 v117, 0xbc800000, v68
	v_fmac_f32_e32 v69, v117, v117
	v_fmac_f32_e32 v116, 0xbc800000, v68
	v_fmac_f32_e32 v69, v116, v116
	v_fmac_f32_e32 v115, 0xbc800000, v68
	v_fmac_f32_e32 v69, v115, v115
	v_fmac_f32_e32 v114, 0xbc800000, v68
	v_fmac_f32_e32 v69, v114, v114
	v_fmac_f32_e32 v113, 0xbc800000, v68
	v_fmac_f32_e32 v69, v113, v113
	v_fmac_f32_e32 v112, 0xbc800000, v68
	v_fmac_f32_e32 v69, v112, v112
	v_fmac_f32_e32 v111, 0xbc800000, v68
	v_fmac_f32_e32 v69, v111, v111
	v_fmac_f32_e32 v110, 0xbc800000, v68
	v_fmac_f32_e32 v69, v110, v110
	v_fmac_f32_e32 v109, 0xbc800000, v68
	v_fmac_f32_e32 v69, v109, v109
	v_fmac_f32_e32 v108, 0xbc800000, v68
	v_fmac_f32_e32 v69, v108, v108
	v_fmac_f32_e32 v107, 0xbc800000, v68
	v_fmac_f32_e32 v69, v107, v107
	v_fmac_f32_e32 v106, 0xbc800000, v68
	v_fmac_f32_e32 v69, v106, v106
	v_fmac_f32_e32 v105, 0xbc800000, v68
	v_fmac_f32_e32 v69, v105, v105
	v_fmac_f32_e32 v104, 0xbc800000, v68
	v_fmac_f32_e32 v69, v104, v104
	v_fmac_f32_e32 v103, 0xbc800000, v68
	v_fmac_f32_e32 v69, v103, v103
	v_fmac_f32_e32 v102, 0xbc800000, v68
	v_fmac_f32_e32 v69, v102, v102
	v_fmac_f32_e32 v101, 0xbc800000, v68
	v_fmac_f32_e32 v69, v101, v101
	v_fmac_f32_e32 v100, 0xbc800000, v68
	v_fmac_f32_e32 v69, v100, v100
	v_fmac_f32_e32 v99, 0xbc800000, v68
	v_fmac_f32_e32 v69, v99, v99
	v_fmac_f32_e32 v98, 0xbc800000, v68
	v_fmac_f32_e32 v69, v98, v98
	v_fmac_f32_e32 v97, 0xbc800000, v68
	v_fmac_f32_e32 v69, v97, v97
	v_fmac_f32_e32 v96, 0xbc800000, v68
	v_fmac_f32_e32 v69, v96, v96
	v_fmac_f32_e32 v95, 0xbc800000, v68
	v_fmac_f32_e32 v69, v95, v95
	v_fmac_f32_e32 v94, 0xbc800000, v68
	v_fmac_f32_e32 v69, v94, v94
	v_fmac_f32_e32 v93, 0xbc800000, v68
	v_fmac_f32_e32 v69, v93, v93
	v_fmac_f32_e32 v92, 0xbc800000, v68
	v_fmac_f32_e32 v69, v92, v92
	v_fmac_f32_e32 v91, 0xbc800000, v68
	v_fmac_f32_e32 v69, v91, v91
	v_fmac_f32_e32 v90, 0xbc800000, v68
	v_fmac_f32_e32 v69, v90, v90
	v_fmac_f32_e32 v89, 0xbc800000, v68
	v_fmac_f32_e32 v69, v89, v89
	v_fmac_f32_e32 v88, 0xbc800000, v68
	v_fmac_f32_e32 v69, v88, v88
	v_fmac_f32_e32 v81, 0xbc800000, v68
	v_fmac_f32_e32 v69, v81, v81
	v_fmac_f32_e32 v73, 0xbc800000, v68
	v_mul_f32_e32 v158, 0x3c800000, v68
	v_fmac_f32_e32 v69, v73, v73
	v_fmac_f32_e32 v72, 0xbc800000, v68
	v_fmac_f32_e32 v69, v72, v72
	v_fmac_f32_e32 v0, 0xbc800000, v68
	v_pk_add_f32 v[70:71], v[66:67], v[158:159] op_sel_hi:[1,0] neg_lo:[0,1] neg_hi:[0,1]
	v_fmac_f32_e32 v69, v0, v0
	v_pk_mul_f32 v[66:67], v[70:71], v[70:71]
	s_nop 0
	v_add_f32_e32 v67, v67, v69
	v_pk_add_f32 v[68:69], v[156:157], v[158:159] op_sel_hi:[1,0] neg_lo:[0,1] neg_hi:[0,1]
	v_add_f32_e32 v151, v66, v67
	v_pk_mul_f32 v[66:67], v[68:69], v[68:69]
	s_nop 0
	v_add_f32_e32 v67, v67, v151
	v_add_f32_e32 v151, v66, v67
	v_pk_add_f32 v[66:67], v[152:153], v[158:159] op_sel_hi:[1,0] neg_lo:[0,1] neg_hi:[0,1]
	global_load_dwordx4 v[156:159], v[78:79], off offset:16
	global_load_dwordx4 v[160:163], v[78:79], off
	global_load_dwordx4 v[196:199], v[78:79], off offset:48
	global_load_dwordx4 v[200:203], v[78:79], off offset:32
	global_load_dwordx4 v[204:207], v[78:79], off offset:80
	global_load_dwordx4 v[208:211], v[78:79], off offset:64
	global_load_dwordx4 v[212:215], v[78:79], off offset:112
	global_load_dwordx4 v[216:219], v[78:79], off offset:96
	global_load_dwordx4 v[220:223], v[78:79], off offset:144
	global_load_dwordx4 v[224:227], v[78:79], off offset:128
	global_load_dwordx4 v[228:231], v[78:79], off offset:176
	global_load_dwordx4 v[232:235], v[78:79], off offset:160
	global_load_dwordx4 v[236:239], v[78:79], off offset:208
	global_load_dwordx4 v[240:243], v[78:79], off offset:192
	global_load_dwordx4 v[244:247], v[78:79], off offset:240
	global_load_dwordx4 v[248:251], v[78:79], off offset:224
	v_pk_mul_f32 v[152:153], v[66:67], v[66:67]
	s_nop 0
	v_add_f32_e32 v151, v153, v151
	v_add_f32_e32 v151, v152, v151
	v_fmamk_f32 v151, v151, 0x3c800000, v177
	v_rsq_f32_e32 v151, v151
	s_nop 0
	v_mul_f32_e32 v150, v150, v151
	v_mul_f32_e32 v149, v149, v151
	v_mul_f32_e32 v148, v148, v151
	v_mul_f32_e32 v146, v146, v151
	v_mul_f32_e32 v137, v137, v151
	v_mul_f32_e32 v136, v136, v151
	v_mul_f32_e32 v135, v135, v151
	v_mul_f32_e32 v134, v134, v151
	v_mul_f32_e32 v133, v133, v151
	v_mul_f32_e32 v132, v132, v151
	v_mul_f32_e32 v131, v131, v151
	v_mul_f32_e32 v130, v130, v151
	v_mul_f32_e32 v129, v129, v151
	v_mul_f32_e32 v128, v128, v151
	v_mul_f32_e32 v127, v127, v151
	v_mul_f32_e32 v126, v126, v151
	v_mul_f32_e32 v125, v125, v151
	v_mul_f32_e32 v124, v124, v151
	v_mul_f32_e32 v123, v123, v151
	v_mul_f32_e32 v122, v122, v151
	v_mul_f32_e32 v121, v121, v151
	v_mul_f32_e32 v120, v120, v151
	v_mul_f32_e32 v119, v119, v151
	v_mul_f32_e32 v118, v118, v151
	v_mul_f32_e32 v117, v117, v151
	v_mul_f32_e32 v116, v116, v151
	v_mul_f32_e32 v115, v115, v151
	v_mul_f32_e32 v114, v114, v151
	v_mul_f32_e32 v113, v113, v151
	v_mul_f32_e32 v112, v112, v151
	v_mul_f32_e32 v111, v111, v151
	v_mul_f32_e32 v110, v110, v151
	v_mul_f32_e32 v109, v109, v151
	v_mul_f32_e32 v108, v108, v151
	v_mul_f32_e32 v107, v107, v151
	v_mul_f32_e32 v106, v106, v151
	v_mul_f32_e32 v105, v105, v151
	v_mul_f32_e32 v104, v104, v151
	v_mul_f32_e32 v103, v103, v151
	v_mul_f32_e32 v102, v102, v151
	v_mul_f32_e32 v101, v101, v151
	v_mul_f32_e32 v100, v100, v151
	v_mul_f32_e32 v99, v99, v151
	v_mul_f32_e32 v98, v98, v151
	v_mul_f32_e32 v97, v97, v151
	v_mul_f32_e32 v96, v96, v151
	v_mul_f32_e32 v95, v95, v151
	v_mul_f32_e32 v94, v94, v151
	v_mul_f32_e32 v93, v93, v151
	v_mul_f32_e32 v92, v92, v151
	v_mul_f32_e32 v91, v91, v151
	v_mul_f32_e32 v90, v90, v151
	v_mul_f32_e32 v89, v89, v151
	v_mul_f32_e32 v88, v88, v151
	v_mul_f32_e32 v81, v81, v151
	v_mul_f32_e32 v73, v73, v151
	v_mul_f32_e32 v0, v0, v151
	v_mul_f32_e32 v72, v72, v151
	v_mul_f32_e32 v70, v70, v151
	v_mul_f32_e32 v68, v68, v151
	v_mul_f32_e32 v66, v66, v151
	s_waitcnt vmcnt(15)
	v_mul_f32_e32 v137, v156, v137
	s_waitcnt vmcnt(14)
	v_mul_f32_e32 v150, v160, v150
	v_mul_f32_e32 v149, v161, v149
	v_cvt_pk_bf16_f32 v160, v150, v149
	v_mul_f32_e32 v148, v162, v148
	v_mul_f32_e32 v146, v163, v146
	v_cvt_pk_bf16_f32 v161, v148, v146
	v_mul_f32_e32 v136, v157, v136
	v_cvt_pk_bf16_f32 v162, v137, v136
	v_mul_f32_e32 v135, v158, v135
	v_mul_f32_e32 v134, v159, v134
	v_cvt_pk_bf16_f32 v163, v135, v134
	ds_write_b128 v86, v[160:163]
	s_waitcnt vmcnt(13)
	v_mul_f32_e32 v129, v196, v129
	s_waitcnt vmcnt(12)
	v_mul_f32_e32 v133, v200, v133
	v_mul_f32_e32 v132, v201, v132
	v_cvt_pk_bf16_f32 v132, v133, v132
	v_mul_f32_e32 v131, v202, v131
	v_mul_f32_e32 v130, v203, v130
	v_cvt_pk_bf16_f32 v133, v131, v130
	v_mul_f32_e32 v128, v197, v128
	v_cvt_pk_bf16_f32 v134, v129, v128
	v_mul_f32_e32 v127, v198, v127
	v_mul_f32_e32 v126, v199, v126
	v_cvt_pk_bf16_f32 v135, v127, v126
	ds_write_b128 v86, v[132:135] offset:16
	s_waitcnt vmcnt(11)
	v_mul_f32_e32 v121, v204, v121
	s_waitcnt vmcnt(10)
	v_mul_f32_e32 v125, v208, v125
	v_mul_f32_e32 v124, v209, v124
	v_cvt_pk_bf16_f32 v124, v125, v124
	v_mul_f32_e32 v123, v210, v123
	v_mul_f32_e32 v122, v211, v122
	v_cvt_pk_bf16_f32 v125, v123, v122
	v_mul_f32_e32 v120, v205, v120
	v_cvt_pk_bf16_f32 v126, v121, v120
	v_mul_f32_e32 v119, v206, v119
	v_mul_f32_e32 v118, v207, v118
	v_cvt_pk_bf16_f32 v127, v119, v118
	ds_write_b128 v86, v[124:127] offset:32
	s_waitcnt vmcnt(9)
	v_mul_f32_e32 v113, v212, v113
	s_waitcnt vmcnt(8)
	v_mul_f32_e32 v117, v216, v117
	v_mul_f32_e32 v116, v217, v116
	v_cvt_pk_bf16_f32 v116, v117, v116
	v_mul_f32_e32 v115, v218, v115
	v_mul_f32_e32 v114, v219, v114
	v_cvt_pk_bf16_f32 v117, v115, v114
	v_mul_f32_e32 v112, v213, v112
	v_cvt_pk_bf16_f32 v118, v113, v112
	v_mul_f32_e32 v111, v214, v111
	v_mul_f32_e32 v110, v215, v110
	v_cvt_pk_bf16_f32 v119, v111, v110
	ds_write_b128 v86, v[116:119] offset:48
	s_waitcnt vmcnt(7)
	v_mul_f32_e32 v105, v220, v105
	s_waitcnt vmcnt(6)
	v_mul_f32_e32 v109, v224, v109
	v_mul_f32_e32 v108, v225, v108
	v_cvt_pk_bf16_f32 v108, v109, v108
	v_mul_f32_e32 v107, v226, v107
	v_mul_f32_e32 v106, v227, v106
	v_cvt_pk_bf16_f32 v109, v107, v106
	v_mul_f32_e32 v104, v221, v104
	v_cvt_pk_bf16_f32 v110, v105, v104
	v_mul_f32_e32 v103, v222, v103
	v_mul_f32_e32 v102, v223, v102
	v_cvt_pk_bf16_f32 v111, v103, v102
	ds_write_b128 v86, v[108:111] offset:64
	s_waitcnt vmcnt(5)
	v_mul_f32_e32 v97, v228, v97
	s_waitcnt vmcnt(4)
	v_mul_f32_e32 v101, v232, v101
	v_mul_f32_e32 v100, v233, v100
	v_cvt_pk_bf16_f32 v100, v101, v100
	v_mul_f32_e32 v99, v234, v99
	v_mul_f32_e32 v98, v235, v98
	v_cvt_pk_bf16_f32 v101, v99, v98
	v_mul_f32_e32 v96, v229, v96
	v_cvt_pk_bf16_f32 v102, v97, v96
	v_mul_f32_e32 v95, v230, v95
	v_mul_f32_e32 v94, v231, v94
	v_cvt_pk_bf16_f32 v103, v95, v94
	ds_write_b128 v86, v[100:103] offset:80
	s_waitcnt vmcnt(3)
	v_mul_f32_e32 v89, v236, v89
	s_waitcnt vmcnt(2)
	v_mul_f32_e32 v93, v240, v93
	v_mul_f32_e32 v92, v241, v92
	v_cvt_pk_bf16_f32 v92, v93, v92
	v_mul_f32_e32 v91, v242, v91
	v_mul_f32_e32 v90, v243, v90
	v_cvt_pk_bf16_f32 v93, v91, v90
	v_mul_f32_e32 v88, v237, v88
	v_cvt_pk_bf16_f32 v94, v89, v88
	v_mul_f32_e32 v81, v238, v81
	v_mul_f32_e32 v73, v239, v73
	v_cvt_pk_bf16_f32 v95, v81, v73
	ds_write_b128 v86, v[92:95] offset:96
	v_mov_b32_e32 v81, v1
	s_waitcnt vmcnt(1)
	v_mul_f32_e32 v68, v245, v68
	s_waitcnt vmcnt(0)
	v_mul_f32_e32 v0, v249, v0
	v_mul_f32_e32 v72, v248, v72
	v_cvt_pk_bf16_f32 v92, v72, v0
	v_mul_f32_e32 v0, v71, v151
	v_mul_f32_e32 v0, v250, v0
	v_mul_f32_e32 v70, v251, v70
	v_cvt_pk_bf16_f32 v93, v0, v70
	v_mul_f32_e32 v0, v69, v151
	v_mul_f32_e32 v0, v244, v0
	v_cvt_pk_bf16_f32 v94, v0, v68
	v_mul_f32_e32 v0, v67, v151
	v_mul_f32_e32 v0, v246, v0
	v_mul_f32_e32 v66, v247, v66
	v_cvt_pk_bf16_f32 v95, v0, v66
	v_add_u32_e32 v0, s11, v84
	ds_write_b128 v86, v[92:95] offset:112
	s_waitcnt lgkmcnt(0)
	s_barrier
	ds_read_b64_tr_b16 v[68:69], v0 offset:576
	ds_read_b64_tr_b16 v[66:67], v0
	ds_read_b64_tr_b16 v[70:71], v0 offset:32
	ds_read_b64_tr_b16 v[72:73], v0 offset:608
	ds_read_b64_tr_b16 v[88:89], v0 offset:64
	ds_read_b64_tr_b16 v[90:91], v0 offset:640
	ds_read_b64_tr_b16 v[92:93], v0 offset:96
	ds_read_b64_tr_b16 v[94:95], v0 offset:672
	s_waitcnt lgkmcnt(6)
	v_mfma_f32_16x16x32_bf16 v[96:99], v[66:69], v[50:53], 0
	s_and_b32 s11, s22, 0xffffff80
	v_mfma_f32_16x16x32_bf16 v[100:103], v[66:69], v[54:57], 0
	v_mfma_f32_16x16x32_bf16 v[104:107], v[66:69], v[58:61], 0
	v_mfma_f32_16x16x32_bf16 v[66:69], v[66:69], v[62:65], 0
	s_waitcnt lgkmcnt(4)
	v_mfma_f32_16x16x32_bf16 v[108:111], v[70:73], v[50:53], 0
	v_mfma_f32_16x16x32_bf16 v[112:115], v[70:73], v[54:57], 0
	v_mfma_f32_16x16x32_bf16 v[116:119], v[70:73], v[58:61], 0
	v_mfma_f32_16x16x32_bf16 v[70:73], v[70:73], v[62:65], 0
	s_waitcnt lgkmcnt(2)
	v_mfma_f32_16x16x32_bf16 v[120:123], v[88:91], v[50:53], 0
	v_mfma_f32_16x16x32_bf16 v[124:127], v[88:91], v[54:57], 0
	v_mfma_f32_16x16x32_bf16 v[128:131], v[88:91], v[58:61], 0
	v_mfma_f32_16x16x32_bf16 v[88:91], v[88:91], v[62:65], 0
	s_waitcnt lgkmcnt(0)
	v_mfma_f32_16x16x32_bf16 v[50:53], v[92:95], v[50:53], 0
	v_mfma_f32_16x16x32_bf16 v[54:57], v[92:95], v[54:57], 0
	v_mfma_f32_16x16x32_bf16 v[58:61], v[92:95], v[58:61], 0
	v_mfma_f32_16x16x32_bf16 v[62:65], v[92:95], v[62:65], 0
	ds_read_b64_tr_b16 v[92:93], v0 offset:4608
	ds_read_b64_tr_b16 v[94:95], v0 offset:5184
	ds_read_b64_tr_b16 v[132:133], v0 offset:4640
	ds_read_b64_tr_b16 v[134:135], v0 offset:5216
	ds_read_b64_tr_b16 v[148:149], v0 offset:4672
	ds_read_b64_tr_b16 v[150:151], v0 offset:5248
	ds_read_b64_tr_b16 v[156:157], v0 offset:4704
	ds_read_b64_tr_b16 v[158:159], v0 offset:5280
	s_waitcnt lgkmcnt(6)
	v_mfma_f32_16x16x32_bf16 v[96:99], v[92:95], v[34:37], v[96:99]
	v_mfma_f32_16x16x32_bf16 v[100:103], v[92:95], v[38:41], v[100:103]
	v_mfma_f32_16x16x32_bf16 v[104:107], v[92:95], v[42:45], v[104:107]
	v_mfma_f32_16x16x32_bf16 v[66:69], v[92:95], v[46:49], v[66:69]
	s_waitcnt lgkmcnt(4)
	v_mfma_f32_16x16x32_bf16 v[92:95], v[132:135], v[34:37], v[108:111]
	v_mfma_f32_16x16x32_bf16 v[108:111], v[132:135], v[38:41], v[112:115]
	v_mfma_f32_16x16x32_bf16 v[112:115], v[132:135], v[42:45], v[116:119]
	v_mfma_f32_16x16x32_bf16 v[70:73], v[132:135], v[46:49], v[70:73]
	s_waitcnt lgkmcnt(2)
	v_mfma_f32_16x16x32_bf16 v[116:119], v[148:151], v[34:37], v[120:123]
	v_mfma_f32_16x16x32_bf16 v[120:123], v[148:151], v[38:41], v[124:127]
	v_mfma_f32_16x16x32_bf16 v[124:127], v[148:151], v[42:45], v[128:131]
	v_mfma_f32_16x16x32_bf16 v[88:91], v[148:151], v[46:49], v[88:91]
	s_waitcnt lgkmcnt(0)
	v_mfma_f32_16x16x32_bf16 v[34:37], v[156:159], v[34:37], v[50:53]
	v_mfma_f32_16x16x32_bf16 v[38:41], v[156:159], v[38:41], v[54:57]
	v_mfma_f32_16x16x32_bf16 v[42:45], v[156:159], v[42:45], v[58:61]
	v_mfma_f32_16x16x32_bf16 v[46:49], v[156:159], v[46:49], v[62:65]
	ds_read_b64_tr_b16 v[50:51], v0 offset:9216
	ds_read_b64_tr_b16 v[52:53], v0 offset:9792
	ds_read_b64_tr_b16 v[54:55], v0 offset:9248
	ds_read_b64_tr_b16 v[56:57], v0 offset:9824
	ds_read_b64_tr_b16 v[58:59], v0 offset:9280
	ds_read_b64_tr_b16 v[60:61], v0 offset:9856
	ds_read_b64_tr_b16 v[62:63], v0 offset:9312
	ds_read_b64_tr_b16 v[64:65], v0 offset:9888
	s_waitcnt lgkmcnt(6)
	v_mfma_f32_16x16x32_bf16 v[96:99], v[50:53], v[2:5], v[96:99]
	v_mfma_f32_16x16x32_bf16 v[100:103], v[50:53], v[6:9], v[100:103]
	v_mfma_f32_16x16x32_bf16 v[104:107], v[50:53], v[10:13], v[104:107]
	v_mfma_f32_16x16x32_bf16 v[50:53], v[50:53], v[14:17], v[66:69]
	s_waitcnt lgkmcnt(4)
	v_mfma_f32_16x16x32_bf16 v[66:69], v[54:57], v[2:5], v[92:95]
	v_mfma_f32_16x16x32_bf16 v[92:95], v[54:57], v[6:9], v[108:111]
	v_mfma_f32_16x16x32_bf16 v[108:111], v[54:57], v[10:13], v[112:115]
	s_waitcnt lgkmcnt(2)
	v_mfma_f32_16x16x32_bf16 v[116:119], v[58:61], v[2:5], v[116:119]
	v_mfma_f32_16x16x32_bf16 v[120:123], v[58:61], v[6:9], v[120:123]
	v_mfma_f32_16x16x32_bf16 v[124:127], v[58:61], v[10:13], v[124:127]
	v_mfma_f32_16x16x32_bf16 v[58:61], v[58:61], v[14:17], v[88:91]
	s_waitcnt lgkmcnt(0)
	v_mfma_f32_16x16x32_bf16 v[88:91], v[62:65], v[6:9], v[38:41]
	v_mfma_f32_16x16x32_bf16 v[128:131], v[62:65], v[10:13], v[42:45]
	ds_read_b64_tr_b16 v[6:7], v0 offset:13824
	ds_read_b64_tr_b16 v[8:9], v0 offset:14400
	ds_read_b64_tr_b16 v[10:11], v0 offset:13856
	ds_read_b64_tr_b16 v[12:13], v0 offset:14432
	ds_read_b64_tr_b16 v[148:149], v0 offset:13888
	ds_read_b64_tr_b16 v[150:151], v0 offset:14464
	ds_read_b64_tr_b16 v[156:157], v0 offset:13920
	ds_read_b64_tr_b16 v[158:159], v0 offset:14496
	v_mfma_f32_16x16x32_bf16 v[2:5], v[62:65], v[2:5], v[34:37]
	v_mfma_f32_16x16x32_bf16 v[112:115], v[54:57], v[14:17], v[70:73]
	v_mfma_f32_16x16x32_bf16 v[132:135], v[62:65], v[14:17], v[46:49]
	s_waitcnt lgkmcnt(6)
	v_mfma_f32_16x16x32_bf16 v[70:73], v[6:9], v[18:21], v[96:99]
	v_mfma_f32_16x16x32_bf16 v[54:57], v[6:9], v[22:25], v[100:103]
	v_mfma_f32_16x16x32_bf16 v[42:45], v[6:9], v[26:29], v[104:107]
	v_mfma_f32_16x16x32_bf16 v[14:17], v[6:9], v[30:33], v[50:53]
	s_waitcnt lgkmcnt(4)
	v_mfma_f32_16x16x32_bf16 v[66:69], v[10:13], v[18:21], v[66:69]
	v_mfma_f32_16x16x32_bf16 v[38:41], v[10:13], v[26:29], v[108:111]
	s_waitcnt lgkmcnt(2)
	v_mfma_f32_16x16x32_bf16 v[62:65], v[148:151], v[18:21], v[116:119]
	v_mfma_f32_16x16x32_bf16 v[34:37], v[148:151], v[26:29], v[124:127]
	v_mfma_f32_16x16x32_bf16 v[6:9], v[148:151], v[30:33], v[58:61]
	s_waitcnt lgkmcnt(0)
	v_mfma_f32_16x16x32_bf16 v[58:61], v[156:159], v[18:21], v[2:5]
	v_mfma_f32_16x16x32_bf16 v[18:21], v[156:159], v[26:29], v[128:131]
	v_or_b32_e32 v28, s11, v80
	v_ashrrev_i32_e32 v29, 31, v28
	v_lshl_or_b32 v26, s10, 6, v144
	v_mfma_f32_16x16x32_bf16 v[50:53], v[10:13], v[22:25], v[92:95]
	v_ashrrev_i32_e32 v27, 31, v26
	v_lshlrev_b64 v[26:27], 1, v[26:27]
	s_ashr_i32 s10, s11, 31
	v_mfma_f32_16x16x32_bf16 v[10:13], v[10:13], v[30:33], v[112:115]
	v_mfma_f32_16x16x32_bf16 v[2:5], v[156:159], v[30:33], v[132:135]
	v_mov_b32_e32 v29, s10
	v_lshl_add_u64 v[28:29], v[28:29], 2, s[50:51]
	v_mfma_f32_16x16x32_bf16 v[46:49], v[148:151], v[22:25], v[120:123]
	v_mfma_f32_16x16x32_bf16 v[22:25], v[156:159], v[22:25], v[88:91]
	v_mov_b32_e32 v195, 0
	v_lshl_add_u64 v[196:197], s[52:53], 0, v[80:81]
	v_mad_u64_u32 v[200:201], s[20:21], v196, s64, v[82:83]
	v_mov_b32_e32 v198, v201
	v_mad_u64_u32 v[198:199], s[20:21], v197, s64, v[198:199]
	v_mov_b32_e32 v201, v198
	v_lshl_add_u64 v[200:201], v[200:201], 0, v[26:27]
	v_lshlrev_b64 v[196:197], 11, v[196:197]
	v_lshl_add_u64 v[208:209], s[70:71], 0, v[196:197]
	v_lshl_add_u64 v[208:209], v[208:209], 0, v[26:27]
	global_load_dword v216, v[28:29], off
	global_load_dwordx2 v[220:221], v[200:201], off offset:3584
	global_load_dwordx2 v[222:223], v[200:201], off offset:3616
	global_load_dwordx2 v[224:225], v[200:201], off offset:3648
	global_load_dwordx2 v[226:227], v[200:201], off offset:3680
	v_or_b32_e32 v194, 16, v80
	v_lshl_add_u64 v[196:197], s[52:53], 0, v[194:195]
	v_mad_u64_u32 v[202:203], s[20:21], v196, s64, v[82:83]
	v_mov_b32_e32 v198, v203
	v_mad_u64_u32 v[198:199], s[20:21], v197, s64, v[198:199]
	v_mov_b32_e32 v203, v198
	v_lshl_add_u64 v[202:203], v[202:203], 0, v[26:27]
	v_lshlrev_b64 v[196:197], 11, v[196:197]
	v_lshl_add_u64 v[210:211], s[70:71], 0, v[196:197]
	v_lshl_add_u64 v[210:211], v[210:211], 0, v[26:27]
	global_load_dword v217, v[28:29], off offset:64
	global_load_dwordx2 v[228:229], v[202:203], off offset:3584
	global_load_dwordx2 v[230:231], v[202:203], off offset:3616
	global_load_dwordx2 v[232:233], v[202:203], off offset:3648
	global_load_dwordx2 v[234:235], v[202:203], off offset:3680
	v_or_b32_e32 v194, 32, v80
	v_lshl_add_u64 v[196:197], s[52:53], 0, v[194:195]
	v_mad_u64_u32 v[204:205], s[20:21], v196, s64, v[82:83]
	v_mov_b32_e32 v198, v205
	v_mad_u64_u32 v[198:199], s[20:21], v197, s64, v[198:199]
	v_mov_b32_e32 v205, v198
	v_lshl_add_u64 v[204:205], v[204:205], 0, v[26:27]
	v_lshlrev_b64 v[196:197], 11, v[196:197]
	v_lshl_add_u64 v[212:213], s[70:71], 0, v[196:197]
	v_lshl_add_u64 v[212:213], v[212:213], 0, v[26:27]
	global_load_dword v218, v[28:29], off offset:128
	global_load_dwordx2 v[236:237], v[204:205], off offset:3584
	global_load_dwordx2 v[238:239], v[204:205], off offset:3616
	global_load_dwordx2 v[240:241], v[204:205], off offset:3648
	global_load_dwordx2 v[242:243], v[204:205], off offset:3680
	v_or_b32_e32 v194, 48, v80
	v_lshl_add_u64 v[196:197], s[52:53], 0, v[194:195]
	v_mad_u64_u32 v[206:207], s[20:21], v196, s64, v[82:83]
	v_mov_b32_e32 v198, v207
	v_mad_u64_u32 v[198:199], s[20:21], v197, s64, v[198:199]
	v_mov_b32_e32 v207, v198
	v_lshl_add_u64 v[206:207], v[206:207], 0, v[26:27]
	v_lshlrev_b64 v[196:197], 11, v[196:197]
	v_lshl_add_u64 v[214:215], s[70:71], 0, v[196:197]
	v_lshl_add_u64 v[214:215], v[214:215], 0, v[26:27]
	global_load_dword v219, v[28:29], off offset:192
	global_load_dwordx2 v[244:245], v[206:207], off offset:3584
	global_load_dwordx2 v[246:247], v[206:207], off offset:3616
	global_load_dwordx2 v[248:249], v[206:207], off offset:3648
	global_load_dwordx2 v[250:251], v[206:207], off offset:3680
	s_add_u32 s52, s52, s24
	s_addc_u32 s53, s53, s25
	s_waitcnt vmcnt(15)
	v_add_f32_e32 v70, v70, v216
	v_add_f32_e32 v71, v71, v216
	v_add_f32_e32 v72, v72, v216
	v_add_f32_e32 v73, v73, v216
	v_lshlrev_b32_e32 v194, 16, v220
	v_and_b32_e32 v195, 0xffff0000, v220
	v_lshlrev_b32_e32 v196, 16, v221
	v_and_b32_e32 v197, 0xffff0000, v221
	v_pk_mul_f32 v[70:71], v[70:71], v[194:195]
	v_pk_mul_f32 v[72:73], v[72:73], v[196:197]
	v_cvt_pk_bf16_f32 v70, v70, v71
	v_cvt_pk_bf16_f32 v71, v72, v73
	global_store_dwordx2 v[208:209], v[70:71], off offset:1536
	v_add_f32_e32 v66, v66, v216
	v_add_f32_e32 v67, v67, v216
	v_add_f32_e32 v68, v68, v216
	v_add_f32_e32 v69, v69, v216
	v_lshlrev_b32_e32 v194, 16, v222
	v_and_b32_e32 v195, 0xffff0000, v222
	v_lshlrev_b32_e32 v196, 16, v223
	v_and_b32_e32 v197, 0xffff0000, v223
	v_pk_mul_f32 v[66:67], v[66:67], v[194:195]
	v_pk_mul_f32 v[68:69], v[68:69], v[196:197]
	v_cvt_pk_bf16_f32 v66, v66, v67
	v_cvt_pk_bf16_f32 v67, v68, v69
	global_store_dwordx2 v[208:209], v[66:67], off offset:1568
	v_add_f32_e32 v62, v62, v216
	v_add_f32_e32 v63, v63, v216
	v_add_f32_e32 v64, v64, v216
	v_add_f32_e32 v65, v65, v216
	v_lshlrev_b32_e32 v194, 16, v224
	v_and_b32_e32 v195, 0xffff0000, v224
	v_lshlrev_b32_e32 v196, 16, v225
	v_and_b32_e32 v197, 0xffff0000, v225
	v_pk_mul_f32 v[62:63], v[62:63], v[194:195]
	v_pk_mul_f32 v[64:65], v[64:65], v[196:197]
	v_cvt_pk_bf16_f32 v62, v62, v63
	v_cvt_pk_bf16_f32 v63, v64, v65
	global_store_dwordx2 v[208:209], v[62:63], off offset:1600
	v_add_f32_e32 v58, v58, v216
	v_add_f32_e32 v59, v59, v216
	v_add_f32_e32 v60, v60, v216
	v_add_f32_e32 v61, v61, v216
	v_lshlrev_b32_e32 v194, 16, v226
	v_and_b32_e32 v195, 0xffff0000, v226
	v_lshlrev_b32_e32 v196, 16, v227
	v_and_b32_e32 v197, 0xffff0000, v227
	v_pk_mul_f32 v[58:59], v[58:59], v[194:195]
	v_pk_mul_f32 v[60:61], v[60:61], v[196:197]
	v_cvt_pk_bf16_f32 v58, v58, v59
	v_cvt_pk_bf16_f32 v59, v60, v61
	global_store_dwordx2 v[208:209], v[58:59], off offset:1632
	s_waitcnt vmcnt(14)
	v_add_f32_e32 v54, v54, v217
	v_add_f32_e32 v55, v55, v217
	v_add_f32_e32 v56, v56, v217
	v_add_f32_e32 v57, v57, v217
	v_lshlrev_b32_e32 v194, 16, v228
	v_and_b32_e32 v195, 0xffff0000, v228
	v_lshlrev_b32_e32 v196, 16, v229
	v_and_b32_e32 v197, 0xffff0000, v229
	v_pk_mul_f32 v[54:55], v[54:55], v[194:195]
	v_pk_mul_f32 v[56:57], v[56:57], v[196:197]
	v_cvt_pk_bf16_f32 v54, v54, v55
	v_cvt_pk_bf16_f32 v55, v56, v57
	global_store_dwordx2 v[210:211], v[54:55], off offset:1536
	v_add_f32_e32 v50, v50, v217
	v_add_f32_e32 v51, v51, v217
	v_add_f32_e32 v52, v52, v217
	v_add_f32_e32 v53, v53, v217
	v_lshlrev_b32_e32 v194, 16, v230
	v_and_b32_e32 v195, 0xffff0000, v230
	v_lshlrev_b32_e32 v196, 16, v231
	v_and_b32_e32 v197, 0xffff0000, v231
	v_pk_mul_f32 v[50:51], v[50:51], v[194:195]
	v_pk_mul_f32 v[52:53], v[52:53], v[196:197]
	v_cvt_pk_bf16_f32 v50, v50, v51
	v_cvt_pk_bf16_f32 v51, v52, v53
	global_store_dwordx2 v[210:211], v[50:51], off offset:1568
	v_add_f32_e32 v46, v46, v217
	v_add_f32_e32 v47, v47, v217
	v_add_f32_e32 v48, v48, v217
	v_add_f32_e32 v49, v49, v217
	v_lshlrev_b32_e32 v194, 16, v232
	v_and_b32_e32 v195, 0xffff0000, v232
	v_lshlrev_b32_e32 v196, 16, v233
	v_and_b32_e32 v197, 0xffff0000, v233
	v_pk_mul_f32 v[46:47], v[46:47], v[194:195]
	v_pk_mul_f32 v[48:49], v[48:49], v[196:197]
	v_cvt_pk_bf16_f32 v46, v46, v47
	v_cvt_pk_bf16_f32 v47, v48, v49
	global_store_dwordx2 v[210:211], v[46:47], off offset:1600
	v_add_f32_e32 v22, v22, v217
	v_add_f32_e32 v23, v23, v217
	v_add_f32_e32 v24, v24, v217
	v_add_f32_e32 v25, v25, v217
	v_lshlrev_b32_e32 v194, 16, v234
	v_and_b32_e32 v195, 0xffff0000, v234
	v_lshlrev_b32_e32 v196, 16, v235
	v_and_b32_e32 v197, 0xffff0000, v235
	v_pk_mul_f32 v[22:23], v[22:23], v[194:195]
	v_pk_mul_f32 v[24:25], v[24:25], v[196:197]
	v_cvt_pk_bf16_f32 v22, v22, v23
	v_cvt_pk_bf16_f32 v23, v24, v25
	global_store_dwordx2 v[210:211], v[22:23], off offset:1632
	s_waitcnt vmcnt(13)
	v_add_f32_e32 v42, v42, v218
	v_add_f32_e32 v43, v43, v218
	v_add_f32_e32 v44, v44, v218
	v_add_f32_e32 v45, v45, v218
	v_lshlrev_b32_e32 v194, 16, v236
	v_and_b32_e32 v195, 0xffff0000, v236
	v_lshlrev_b32_e32 v196, 16, v237
	v_and_b32_e32 v197, 0xffff0000, v237
	v_pk_mul_f32 v[42:43], v[42:43], v[194:195]
	v_pk_mul_f32 v[44:45], v[44:45], v[196:197]
	v_cvt_pk_bf16_f32 v42, v42, v43
	v_cvt_pk_bf16_f32 v43, v44, v45
	global_store_dwordx2 v[212:213], v[42:43], off offset:1536
	v_add_f32_e32 v38, v38, v218
	v_add_f32_e32 v39, v39, v218
	v_add_f32_e32 v40, v40, v218
	v_add_f32_e32 v41, v41, v218
	v_lshlrev_b32_e32 v194, 16, v238
	v_and_b32_e32 v195, 0xffff0000, v238
	v_lshlrev_b32_e32 v196, 16, v239
	v_and_b32_e32 v197, 0xffff0000, v239
	v_pk_mul_f32 v[38:39], v[38:39], v[194:195]
	v_pk_mul_f32 v[40:41], v[40:41], v[196:197]
	v_cvt_pk_bf16_f32 v38, v38, v39
	v_cvt_pk_bf16_f32 v39, v40, v41
	global_store_dwordx2 v[212:213], v[38:39], off offset:1568
	v_add_f32_e32 v34, v34, v218
	v_add_f32_e32 v35, v35, v218
	v_add_f32_e32 v36, v36, v218
	v_add_f32_e32 v37, v37, v218
	v_lshlrev_b32_e32 v194, 16, v240
	v_and_b32_e32 v195, 0xffff0000, v240
	v_lshlrev_b32_e32 v196, 16, v241
	v_and_b32_e32 v197, 0xffff0000, v241
	v_pk_mul_f32 v[34:35], v[34:35], v[194:195]
	v_pk_mul_f32 v[36:37], v[36:37], v[196:197]
	v_cvt_pk_bf16_f32 v34, v34, v35
	v_cvt_pk_bf16_f32 v35, v36, v37
	global_store_dwordx2 v[212:213], v[34:35], off offset:1600
	v_add_f32_e32 v18, v18, v218
	v_add_f32_e32 v19, v19, v218
	v_add_f32_e32 v20, v20, v218
	v_add_f32_e32 v21, v21, v218
	v_lshlrev_b32_e32 v194, 16, v242
	v_and_b32_e32 v195, 0xffff0000, v242
	v_lshlrev_b32_e32 v196, 16, v243
	v_and_b32_e32 v197, 0xffff0000, v243
	v_pk_mul_f32 v[18:19], v[18:19], v[194:195]
	v_pk_mul_f32 v[20:21], v[20:21], v[196:197]
	v_cvt_pk_bf16_f32 v18, v18, v19
	v_cvt_pk_bf16_f32 v19, v20, v21
	global_store_dwordx2 v[212:213], v[18:19], off offset:1632
	s_waitcnt vmcnt(12)
	v_add_f32_e32 v14, v14, v219
	v_add_f32_e32 v15, v15, v219
	v_add_f32_e32 v16, v16, v219
	v_add_f32_e32 v17, v17, v219
	v_lshlrev_b32_e32 v194, 16, v244
	v_and_b32_e32 v195, 0xffff0000, v244
	v_lshlrev_b32_e32 v196, 16, v245
	v_and_b32_e32 v197, 0xffff0000, v245
	v_pk_mul_f32 v[14:15], v[14:15], v[194:195]
	v_pk_mul_f32 v[16:17], v[16:17], v[196:197]
	v_cvt_pk_bf16_f32 v14, v14, v15
	v_cvt_pk_bf16_f32 v15, v16, v17
	global_store_dwordx2 v[214:215], v[14:15], off offset:1536
	v_add_f32_e32 v10, v10, v219
	v_add_f32_e32 v11, v11, v219
	v_add_f32_e32 v12, v12, v219
	v_add_f32_e32 v13, v13, v219
	v_lshlrev_b32_e32 v194, 16, v246
	v_and_b32_e32 v195, 0xffff0000, v246
	v_lshlrev_b32_e32 v196, 16, v247
	v_and_b32_e32 v197, 0xffff0000, v247
	v_pk_mul_f32 v[10:11], v[10:11], v[194:195]
	v_pk_mul_f32 v[12:13], v[12:13], v[196:197]
	v_cvt_pk_bf16_f32 v10, v10, v11
	v_cvt_pk_bf16_f32 v11, v12, v13
	global_store_dwordx2 v[214:215], v[10:11], off offset:1568
	v_add_f32_e32 v6, v6, v219
	v_add_f32_e32 v7, v7, v219
	v_add_f32_e32 v8, v8, v219
	v_add_f32_e32 v9, v9, v219
	v_lshlrev_b32_e32 v194, 16, v248
	v_and_b32_e32 v195, 0xffff0000, v248
	v_lshlrev_b32_e32 v196, 16, v249
	v_and_b32_e32 v197, 0xffff0000, v249
	v_pk_mul_f32 v[6:7], v[6:7], v[194:195]
	v_pk_mul_f32 v[8:9], v[8:9], v[196:197]
	v_cvt_pk_bf16_f32 v6, v6, v7
	v_cvt_pk_bf16_f32 v7, v8, v9
	global_store_dwordx2 v[214:215], v[6:7], off offset:1600
	v_add_f32_e32 v2, v2, v219
	v_add_f32_e32 v3, v3, v219
	v_add_f32_e32 v4, v4, v219
	v_add_f32_e32 v5, v5, v219
	v_lshlrev_b32_e32 v194, 16, v250
	v_and_b32_e32 v195, 0xffff0000, v250
	v_lshlrev_b32_e32 v196, 16, v251
	v_and_b32_e32 v197, 0xffff0000, v251
	v_pk_mul_f32 v[2:3], v[2:3], v[194:195]
	v_pk_mul_f32 v[4:5], v[4:5], v[196:197]
	v_cvt_pk_bf16_f32 v2, v2, v3
	v_cvt_pk_bf16_f32 v3, v4, v5
	global_store_dwordx2 v[214:215], v[2:3], off offset:1632
	s_cmp_ge_i32 s16, s2
	s_barrier
	s_cbranch_scc0 .LBB0_257
	s_branch .LBB0_254

.LBB0_729:
	s_waitcnt vmcnt(3)
	v_mul_f32_e32 v0, v47, v47
	v_mul_f32_e32 v64, v49, v49
	v_fmac_f32_e32 v0, v46, v46
	v_fmac_f32_e32 v64, v48, v48
	v_add_f32_e32 v0, v0, v64
	s_waitcnt vmcnt(2)
	v_mul_f32_e32 v64, v43, v43
	v_mul_f32_e32 v65, v45, v45
	v_fmac_f32_e32 v64, v42, v42
	v_fmac_f32_e32 v65, v44, v44
	v_add_f32_e32 v64, v64, v65
	v_add_f32_e32 v0, v0, v64
	s_waitcnt vmcnt(1)
	v_mul_f32_e32 v64, v39, v39
	v_mul_f32_e32 v65, v41, v41
	v_fmac_f32_e32 v64, v38, v38
	v_fmac_f32_e32 v65, v40, v40
	v_add_f32_e32 v64, v64, v65
	v_add_f32_e32 v0, v0, v64
	s_waitcnt vmcnt(0)
	v_mul_f32_e32 v64, v35, v35
	v_mul_f32_e32 v65, v37, v37
	v_fmac_f32_e32 v64, v34, v34
	v_fmac_f32_e32 v65, v36, v36
	v_add_f32_e32 v64, v64, v65
	v_add_f32_e32 v0, v0, v64
	s_nop 1
	v_add_f32_dpp v0, v0, v0 quad_perm:[1,0,3,2] row_mask:0xf bank_mask:0xf
	s_nop 1
	v_add_f32_dpp v0, v0, v0 quad_perm:[2,3,0,1] row_mask:0xf bank_mask:0xf
	s_nop 1
	v_add_f32_dpp v0, v0, v0 row_half_mirror row_mask:0xf bank_mask:0xf
	s_nop 1
	v_add_f32_dpp v0, v0, v0 row_mirror row_mask:0xf bank_mask:0xf
	v_mov_b32_e32 v64, v0
	s_nop 1
	v_permlane16_swap_b32_e32 v0, v64
	v_add_f32_e32 v0, v0, v64
	v_mov_b32_e32 v64, v0
	s_nop 1
	v_permlane32_swap_b32_e32 v0, v64
	v_add_f32_e32 v0, v0, v64
	v_readlane_b32 s20, v255, 5
	v_readlane_b32 s21, v255, 6
	s_add_i32 s2, s2, s82
	s_cmp_gt_i32 s2, 0x81ff
	v_lshl_add_u64 v[52:53], v[52:53], 0, s[20:21]
	v_readlane_b32 s20, v254, 57
	v_readlane_b32 s21, v254, 58
	v_fmamk_f32 v0, v0, 0x3a800000, v177
	v_rsq_f32_e32 v0, v0
	v_lshl_add_u64 v[64:65], s[28:29], 0, v[54:55]
	v_lshl_add_u64 v[54:55], v[54:55], 0, s[20:21]
	v_pk_mul_f32 v[46:47], v[46:47], v[0:1] op_sel_hi:[1,0]
	v_pk_mul_f32 v[42:43], v[42:43], v[0:1] op_sel_hi:[1,0]
	v_pk_mul_f32 v[44:45], v[44:45], v[0:1] op_sel_hi:[1,0]
	v_pk_fma_f32 v[46:47], v[2:3], v[46:47], v[30:31]
	v_pk_mul_f32 v[48:49], v[48:49], v[0:1] op_sel_hi:[1,0]
	v_pk_fma_f32 v[66:67], v[8:9], v[44:45], v[24:25]
	v_pk_fma_f32 v[44:45], v[6:7], v[42:43], v[22:23]
	v_cvt_pk_bf16_f32 v42, v46, v47
	v_add_co_u32_e32 v46, vcc, s11, v64
	v_pk_fma_f32 v[48:49], v[4:5], v[48:49], v[32:33]
	s_nop 0
	v_addc_co_u32_e32 v47, vcc, 0, v65, vcc
	v_cvt_pk_bf16_f32 v43, v48, v49
	v_pk_mul_f32 v[34:35], v[34:35], v[0:1] op_sel_hi:[1,0]
	v_pk_mul_f32 v[36:37], v[36:37], v[0:1] op_sel_hi:[1,0]
	v_cvt_pk_bf16_f32 v44, v44, v45
	v_cvt_pk_bf16_f32 v45, v66, v67
	global_store_dwordx4 v[46:47], v[42:45], off
	v_pk_mul_f32 v[38:39], v[38:39], v[0:1] op_sel_hi:[1,0]
	v_pk_mul_f32 v[40:41], v[40:41], v[0:1] op_sel_hi:[1,0]
	v_pk_fma_f32 v[42:43], v[16:17], v[36:37], v[20:21]
	v_pk_fma_f32 v[36:37], v[14:15], v[34:35], v[18:19]
	v_pk_fma_f32 v[40:41], v[12:13], v[40:41], v[28:29]
	v_pk_fma_f32 v[38:39], v[10:11], v[38:39], v[26:27]
	s_nop 0
	v_cvt_pk_bf16_f32 v34, v38, v39
	v_cvt_pk_bf16_f32 v35, v40, v41
	v_cvt_pk_bf16_f32 v36, v36, v37
	v_cvt_pk_bf16_f32 v37, v42, v43
	global_store_dwordx4 v[46:47], v[34:37], off offset:1024
	s_cbranch_scc1 .LBB0_732

.LBB0_736:
	s_waitcnt vmcnt(2)
	v_mul_f32_e32 v0, v47, v47
	v_mul_f32_e32 v62, v49, v49
	v_fmac_f32_e32 v0, v46, v46
	v_fmac_f32_e32 v62, v48, v48
	v_add_f32_e32 v0, v0, v62
	v_mul_f32_e32 v62, v43, v43
	v_mul_f32_e32 v63, v45, v45
	v_fmac_f32_e32 v62, v42, v42
	v_fmac_f32_e32 v63, v44, v44
	v_add_f32_e32 v62, v62, v63
	v_add_f32_e32 v0, v0, v62
	s_waitcnt vmcnt(0)
	v_mul_f32_e32 v62, v39, v39
	v_mul_f32_e32 v63, v41, v41
	v_fmac_f32_e32 v62, v38, v38
	v_fmac_f32_e32 v63, v40, v40
	v_add_f32_e32 v62, v62, v63
	v_add_f32_e32 v0, v0, v62
	v_mul_f32_e32 v62, v35, v35
	v_mul_f32_e32 v63, v37, v37
	v_fmac_f32_e32 v62, v34, v34
	v_fmac_f32_e32 v63, v36, v36
	v_add_f32_e32 v62, v62, v63
	v_add_f32_e32 v0, v0, v62
	s_nop 1
	v_add_f32_dpp v0, v0, v0 quad_perm:[1,0,3,2] row_mask:0xf bank_mask:0xf
	s_nop 1
	v_add_f32_dpp v0, v0, v0 quad_perm:[2,3,0,1] row_mask:0xf bank_mask:0xf
	s_nop 1
	v_add_f32_dpp v0, v0, v0 row_half_mirror row_mask:0xf bank_mask:0xf
	s_nop 1
	v_add_f32_dpp v0, v0, v0 row_mirror row_mask:0xf bank_mask:0xf
	v_mov_b32_e32 v62, v0
	s_nop 1
	v_permlane16_swap_b32_e32 v0, v62
	v_add_f32_e32 v0, v0, v62
	v_mov_b32_e32 v62, v0
	s_nop 1
	v_permlane32_swap_b32_e32 v0, v62
	v_add_f32_e32 v0, v0, v62
	s_add_u32 s2, s2, s82
	v_readlane_b32 s20, v254, 57
	s_addc_u32 s3, s3, s83
	v_readlane_b32 s21, v254, 58
	s_cmp_gt_i32 s2, 0x81ff
	v_fmamk_f32 v0, v0, 0x3a800000, v177
	v_rsq_f32_e32 v0, v0
	s_nop 0
	v_pk_mul_f32 v[46:47], v[46:47], v[0:1] op_sel_hi:[1,0]
	v_pk_mul_f32 v[48:49], v[48:49], v[0:1] op_sel_hi:[1,0]
	v_pk_mul_f32 v[42:43], v[42:43], v[0:1] op_sel_hi:[1,0]
	v_pk_mul_f32 v[44:45], v[44:45], v[0:1] op_sel_hi:[1,0]
	v_pk_fma_f32 v[48:49], v[4:5], v[48:49], v[32:33]
	v_pk_fma_f32 v[46:47], v[2:3], v[46:47], v[30:31]
	v_pk_fma_f32 v[62:63], v[8:9], v[44:45], v[24:25]
	v_pk_fma_f32 v[44:45], v[6:7], v[42:43], v[22:23]
	v_cvt_pk_bf16_f32 v42, v46, v47
	v_cvt_pk_bf16_f32 v43, v48, v49
	v_pk_mul_f32 v[34:35], v[34:35], v[0:1] op_sel_hi:[1,0]
	v_pk_mul_f32 v[36:37], v[36:37], v[0:1] op_sel_hi:[1,0]
	v_pk_mul_f32 v[38:39], v[38:39], v[0:1] op_sel_hi:[1,0]
	v_cvt_pk_bf16_f32 v44, v44, v45
	v_cvt_pk_bf16_f32 v45, v62, v63
	global_store_dwordx4 v[54:55], v[42:45], off
	v_pk_mul_f32 v[40:41], v[40:41], v[0:1] op_sel_hi:[1,0]
	v_pk_fma_f32 v[38:39], v[10:11], v[38:39], v[26:27]
	v_pk_fma_f32 v[42:43], v[16:17], v[36:37], v[20:21]
	v_pk_fma_f32 v[36:37], v[14:15], v[34:35], v[18:19]
	v_pk_fma_f32 v[40:41], v[12:13], v[40:41], v[28:29]
	v_cvt_pk_bf16_f32 v34, v38, v39
	s_nop 0
	v_cvt_pk_bf16_f32 v35, v40, v41
	v_cvt_pk_bf16_f32 v36, v36, v37
	v_cvt_pk_bf16_f32 v37, v42, v43
	global_store_dwordx4 v[54:55], v[34:37], off offset:1024
	v_lshl_add_u64 v[54:55], v[54:55], 0, s[20:21]
	s_cbranch_scc1 .LBB0_739

.LBB0_743:
	v_lshl_add_u64 v[24:25], s[2:3], 0, v[0:1]
	v_add_co_u32_e32 v32, vcc, 0x3200000, v24
	v_lshl_add_u64 v[28:29], v[24:25], 0, s[22:23]
	v_lshl_add_u64 v[36:37], v[24:25], 0, s[26:27]
	v_addc_co_u32_e32 v33, vcc, 0, v25, vcc
	global_load_dwordx4 v[24:27], v[32:33], off
	s_nop 0
	global_load_dwordx4 v[28:31], v[28:29], off offset:16
	s_nop 0
	global_load_dwordx4 v[32:35], v[32:33], off offset:2048
	s_nop 0
	global_load_dwordx4 v[36:39], v[36:37], off offset:16
	s_add_i32 s15, s15, s82
	s_add_u32 s2, s2, s20
	s_addc_u32 s3, s3, s21
	v_lshl_add_u64 v[40:41], s[10:11], 0, v[0:1]
	s_add_u32 s10, s10, s20
	s_addc_u32 s11, s11, s21
	s_cmpk_gt_i32 s15, 0x7fff
	s_waitcnt vmcnt(3)
	v_pk_mul_f32 v[42:43], v[26:27], v[26:27]
	v_pk_mul_f32 v[44:45], v[24:25], v[24:25]
	s_waitcnt vmcnt(2)
	v_pk_mul_f32 v[46:47], v[30:31], v[30:31]
	v_pk_mul_f32 v[48:49], v[28:29], v[28:29]
	v_pk_mov_b32 v[54:55], v[44:45], v[42:43] op_sel:[1,0]
	v_mov_b32_e32 v45, v43
	v_pk_mov_b32 v[42:43], v[48:49], v[46:47] op_sel:[1,0]
	v_mov_b32_e32 v49, v47
	s_waitcnt vmcnt(0)
	v_mul_f32_e32 v53, v36, v36
	v_mul_f32_e32 v50, v33, v33
	v_mul_f32_e32 v52, v35, v35
	v_pk_add_f32 v[44:45], v[54:55], v[44:45]
	v_pk_add_f32 v[42:43], v[42:43], v[48:49]
	v_mul_f32_e32 v56, v37, v37
	v_mul_f32_e32 v57, v38, v38
	v_mul_f32_e32 v58, v39, v39
	v_pk_fma_f32 v[46:47], v[32:33], v[32:33], v[50:51] op_sel_hi:[1,1,0]
	v_pk_fma_f32 v[50:51], v[34:35], v[34:35], v[52:53] op_sel_hi:[1,1,0]
	v_pk_add_f32 v[44:45], v[44:45], v[44:45] op_sel:[0,1] op_sel_hi:[1,0]
	v_pk_add_f32 v[42:43], v[42:43], v[42:43] op_sel:[0,1] op_sel_hi:[1,0]
	v_mov_b32_e32 v47, v57
	v_mov_b32_e32 v51, v58
	v_mov_b32_e32 v45, v53
	v_mov_b32_e32 v43, v56
	v_pk_add_f32 v[46:47], v[46:47], v[50:51]
	v_pk_add_f32 v[42:43], v[44:45], v[42:43]
	s_nop 0
	v_pk_add_f32 v[42:43], v[42:43], v[46:47]
	s_nop 0
	v_add_f32_e32 v42, v42, v43
	s_nop 1
	v_add_f32_dpp v42, v42, v42 quad_perm:[1,0,3,2] row_mask:0xf bank_mask:0xf
	s_nop 1
	v_add_f32_dpp v42, v42, v42 quad_perm:[2,3,0,1] row_mask:0xf bank_mask:0xf
	s_nop 1
	v_add_f32_dpp v42, v42, v42 row_half_mirror row_mask:0xf bank_mask:0xf
	s_nop 1
	v_add_f32_dpp v42, v42, v42 row_mirror row_mask:0xf bank_mask:0xf
	v_mov_b32_e32 v43, v42
	s_nop 1
	v_permlane16_swap_b32_e32 v42, v43
	v_add_f32_e32 v42, v42, v43
	v_mov_b32_e32 v43, v42
	s_nop 1
	v_permlane32_swap_b32_e32 v42, v43
	v_add_f32_e32 v42, v42, v43
	v_fmamk_f32 v42, v42, 0x3a800000, v177
	v_rsq_f32_e32 v42, v42
	s_nop 0
	v_pk_mul_f32 v[24:25], v[24:25], v[42:43] op_sel_hi:[1,0]
	v_pk_mul_f32 v[26:27], v[26:27], v[42:43] op_sel_hi:[1,0]
	v_pk_mul_f32 v[28:29], v[28:29], v[42:43] op_sel_hi:[1,0]
	v_pk_mul_f32 v[30:31], v[30:31], v[42:43] op_sel_hi:[1,0]
	v_pk_mul_f32 v[32:33], v[32:33], v[42:43] op_sel_hi:[1,0]
	v_pk_mul_f32 v[34:35], v[34:35], v[42:43] op_sel_hi:[1,0]
	v_pk_mul_f32 v[36:37], v[36:37], v[42:43] op_sel_hi:[1,0]
	v_pk_mul_f32 v[38:39], v[38:39], v[42:43] op_sel_hi:[1,0]
	v_pk_mul_f32 v[26:27], v[8:9], v[26:27]
	v_pk_mul_f32 v[24:25], v[6:7], v[24:25]
	v_pk_mul_f32 v[30:31], v[4:5], v[30:31]
	v_pk_mul_f32 v[28:29], v[2:3], v[28:29]
	v_pk_mul_f32 v[34:35], v[16:17], v[34:35]
	v_pk_mul_f32 v[32:33], v[14:15], v[32:33]
	v_pk_mul_f32 v[38:39], v[12:13], v[38:39]
	v_pk_mul_f32 v[36:37], v[10:11], v[36:37]
	global_store_dwordx4 v[40:41], v[24:27], off
	global_store_dwordx4 v[40:41], v[28:31], off offset:16
	global_store_dwordx4 v[40:41], v[32:35], off offset:2048
	global_store_dwordx4 v[40:41], v[36:39], off offset:2064
	s_cbranch_scc0 .LBB0_743
